# prompt scan: the four workgroups of a sequence now share blockIdx % 8 (same XCD under round-robin placement) so the XCD L2 serves three of the four fragment streams
# speedup vs baseline: 1.0014x; 1.0014x over previous
; #define LAS __attribute__((address_space(3)))
; __device__ __forceinline__ void hg_seq(const Frame& F, unsigned char* ws, const float* s0, float* sout, float* Og, int seq, bool sample, int vs_base, int nvs) {
;     LAS unsigned char* ring = F.lds;
;     const int tid = F.tid, lane = F.lane, vs = vs_base + F.wave, r = lane & 15, q = lane >> 4;
;     const bool active = F.wave < nvs, vload = (unsigned)((tid >> 6) - vs_base) < (unsigned)nvs;
;     int nch, nvalid, t0, h; const unsigned char *qf, *vf, *lf; int qp, lp; size_t qstep, lstep;
;     if (!sample) { const int b = seq >> 2; h = seq & 3; t0 = b * 2048; nch = 64; nvalid = 32; const size_t e0 = (size_t)t0 * DA + h * 128;
;         qf = ws + WS_Q + e0 * 2; vf = ws + WS_V + e0 * 2; lf = ws + WS_LOGF + e0 * 4; qp = 1024; lp = 2048; qstep = 32 * 1024; lstep = 32 * 2048; }
;     else { const int b = seq >> 2; h = seq & 3; t0 = TP + b * 8; nch = 1; nvalid = 8; const unsigned char* base = (const unsigned char*)sout + (size_t)seq * 65536;
;         qf = base; vf = base + 8192; lf = base + 16384; qp = 256; lp = 512; qstep = 0; lstep = 0; }
;     const size_t offq = (size_t)(tid >> 4) * qp + (tid & 15) * 16, offl0 = (size_t)(tid >> 5) * lp + (tid & 31) * 16, offl1 = (size_t)(16 + (tid >> 5)) * lp + (tid & 31) * 16, offl1c = tid < 160 ? offl1 : offl0;
;     {
;     f32x4 S[8];
;     if (sample && active) {
; #pragma unroll
;         for (int kb = 0; kb < 8; ++kb)
; #pragma unroll
;             for (int i = 0; i < 4; ++i) S[kb][i] = s0[((size_t)seq * 128 + 16 * kb + 4 * q + i) * 128 + 16 * vs + r];
;     } else {
; #pragma unroll
;         for (int kb = 0; kb < 8; ++kb) S[kb] = (f32x4){0.f, 0.f, 0.f, 0.f};
;     }
;     float* Ob = Og + (size_t)t0 * DA + h * 128;
; __global__ void __launch_bounds__(NWAVES * 64, 2) mk_fwd(Args args) {
;     ...
;             if (bid < NSCAN) hg_seq(F, ws, nullptr, out + OUT_SHP, Og, bid >> 2, false, 2 * (bid & 3), 2);
.LBB0_1194:
	s_and_b64 vcc, exec, s[6:7]
	s_cbranch_vccz .LBB0_1246
	s_mov_b64 exec, -1
	s_and_b32 s6, s2, 7
	s_lshr_b32 s7, s2, 5
	s_bfe_u32 s8, s2, 0x20003
	s_lshl_b32 s8, s8, 1
	s_lshl_b32 s9, s6, 21
	s_lshl_b32 s3, s7, 8
	s_add_u32 s9, s9, s3
	s_add_u32 s10, s22, s9
	s_addc_u32 s11, s23, 0
	s_lshl_b32 s9, s9, 1
	s_add_u32 s12, s22, s9
	s_addc_u32 s13, s23, 0
	s_add_u32 s14, s10, 0xb980000
	s_addc_u32 s15, s11, 0
	s_add_u32 s16, s10, 0xca80000
	s_addc_u32 s17, s11, 0
	s_add_u32 s34, s12, 0xdb80000
	s_addc_u32 s35, s13, 0
	s_add_u32 s36, s12, 0x2080000
	s_addc_u32 s37, s13, 0
	s_mov_b32 s62, 0
	s_cmp_lt_u32 s50, 2
	s_cbranch_scc0 .Lscan_loader
	v_lshlrev_b32_e32 v160, 4, v189
	s_lshl_b32 s3, s50, 10
	v_add_u32_e32 v161, s3, v160
	v_lshrrev_b32_e32 v1, 4, v189
	v_lshlrev_b32_e32 v163, 4, v1
	s_add_i32 s3, s8, s50
	s_lshl_b32 s3, s3, 4
	v_and_b32_e32 v2, 15, v189
	v_add_u32_e32 v2, s3, v2
	v_lshlrev_b32_e32 v2, 2, v2
	v_lshl_add_u32 v172, v1, 13, v2
	v_add_u32_e32 v173, 0x1000, v172
	v_add_u32_e32 v174, 0x8000, v172
	v_add_u32_e32 v175, 0x9000, v172
	v_lshl_add_u32 v176, v1, 11, v2
	v_mov_b32_e32 v4, 0
	v_mov_b32_e32 v5, 0
	v_mov_b32_e32 v6, 0
	v_mov_b32_e32 v7, 0
	v_mov_b32_e32 v8, 0
	v_mov_b32_e32 v9, 0
	v_mov_b32_e32 v10, 0
	v_mov_b32_e32 v11, 0
	v_mov_b32_e32 v12, 0
	v_mov_b32_e32 v13, 0
	v_mov_b32_e32 v14, 0
	v_mov_b32_e32 v15, 0
	v_mov_b32_e32 v16, 0
	v_mov_b32_e32 v17, 0
	v_mov_b32_e32 v18, 0
	v_mov_b32_e32 v19, 0
	v_mov_b32_e32 v20, 0
	v_mov_b32_e32 v21, 0
	v_mov_b32_e32 v22, 0
	v_mov_b32_e32 v23, 0
	v_mov_b32_e32 v24, 0
	v_mov_b32_e32 v25, 0
	v_mov_b32_e32 v26, 0
	v_mov_b32_e32 v27, 0
	v_mov_b32_e32 v28, 0
	v_mov_b32_e32 v29, 0
	v_mov_b32_e32 v30, 0
	v_mov_b32_e32 v31, 0
	v_mov_b32_e32 v32, 0
	v_mov_b32_e32 v33, 0
	v_mov_b32_e32 v34, 0
	v_mov_b32_e32 v35, 0
	s_mov_b32 s60, 0
	s_barrier
; #define LAS __attribute__((address_space(3)))
; __device__ __forceinline__ unsigned pk2(float lo, float hi) { const f32x2_t_ v = {lo, hi}; return __builtin_bit_cast(unsigned, __builtin_convertvector(v, bf16x2_t_)); }
; __device__ __forceinline__ void hg_chunk(const LAS unsigned char* sl, f32x4 (&S)[8], float* Orow, int nvalid, int vs, int lane) {
;     const int r = lane & 15, q = lane >> 4;
;     const bf16x8 vfr = *(const LAS bf16x8*)(sl + 16384 + ((vs * 64 + lane) << 4));
;     f32x4 o0 = {0.f, 0.f, 0.f, 0.f}, o1 = {0.f, 0.f, 0.f, 0.f};
;     { const bf16x8 s0 = *(const LAS bf16x8*)(sl + 24576 + (lane << 4)), s1 = *(const LAS bf16x8*)(sl + 24576 + ((64 + lane) << 4));
;       o0 = __builtin_amdgcn_mfma_f32_16x16x32_bf16(s0, vfr, o0, 0, 0, 0); o1 = __builtin_amdgcn_mfma_f32_16x16x32_bf16(s1, vfr, o1, 0, 0, 0); }
; #pragma unroll
;     for (int m = 0; m < 4; ++m) {
;         v4u sw; sw.x = pk2(S[2 * m][0], S[2 * m][1]); sw.y = pk2(S[2 * m][2], S[2 * m][3]); sw.z = pk2(S[2 * m + 1][0], S[2 * m + 1][1]); sw.w = pk2(S[2 * m + 1][2], S[2 * m + 1][3]);
;         const bf16x8 sb = __builtin_bit_cast(bf16x8, sw);
;         const bf16x8 a0 = *(const LAS bf16x8*)(sl + ((m * 64 + lane) << 4)), a1 = *(const LAS bf16x8*)(sl + (((4 + m) * 64 + lane) << 4));
;         o0 = __builtin_amdgcn_mfma_f32_16x16x32_bf16(a0, sb, o0, 0, 0, 0); o1 = __builtin_amdgcn_mfma_f32_16x16x32_bf16(a1, sb, o1, 0, 0, 0);
;     }
; #pragma unroll
;     for (int i = 0; i < 4; ++i) { const int c0 = 4 * q + i;
;         if (c0 < nvalid) Orow[(size_t)c0 * DA + 16 * vs + r] = o0[i];
;         if (c0 + 16 < nvalid) Orow[(size_t)(c0 + 16) * DA + 16 * vs + r] = o1[i]; }
; #pragma unroll
;     for (int kb = 0; kb < 8; ++kb) { const f32x4 d = *(const LAS f32x4*)(sl + 26624 + ((16 * kb + 4 * q) << 2));
;         const bf16x8 ke = *(const LAS bf16x8*)(sl + 8192 + ((kb * 64 + lane) << 4));
;         S[kb] = __builtin_amdgcn_mfma_f32_16x16x32_bf16(ke, vfr, S[kb] * d, 0, 0, 0); }
; }
; __device__ __forceinline__ void hg_seq(const Frame& F, unsigned char* ws, const float* s0, float* sout, float* Og, int seq, bool sample, int vs_base, int nvs) {
;     ...
;     if (active) {
; #pragma unroll
;     for (int kb = 0; kb < 8; ++kb)
; #pragma unroll
;         for (int i = 0; i < 4; ++i) sout[((size_t)seq * 128 + 16 * kb + 4 * q + i) * 128 + 16 * vs + r] = S[kb][i];
;     }
.Lscan_act_loop:
	v_add_u32_e32 v1, s60, v160
	v_add_u32_e32 v2, s60, v161
	v_add_u32_e32 v3, s60, v163
	ds_read_b128 v[128:131], v3 offset:20480
	ds_read_b128 v[132:135], v3 offset:20544
	ds_read_b128 v[136:139], v3 offset:20608
	ds_read_b128 v[140:143], v3 offset:20672
	ds_read_b128 v[144:147], v3 offset:20736
	ds_read_b128 v[148:151], v3 offset:20800
	ds_read_b128 v[152:155], v3 offset:20864
	ds_read_b128 v[156:159], v3 offset:20928
	ds_read_b128 v[52:55], v2 offset:16384
	ds_read_b128 v[56:59], v1 offset:18432
	ds_read_b128 v[60:63], v1 offset:19456
	ds_read_b128 v[64:67], v1 offset:0
	ds_read_b128 v[80:83], v1 offset:4096
	ds_read_b128 v[68:71], v1 offset:1024
	ds_read_b128 v[84:87], v1 offset:5120
	v_cvt_pk_bf16_f32 v36, v4, v5
	v_cvt_pk_bf16_f32 v37, v6, v7
	v_cvt_pk_bf16_f32 v38, v8, v9
	v_cvt_pk_bf16_f32 v39, v10, v11
	v_cvt_pk_bf16_f32 v40, v12, v13
	v_cvt_pk_bf16_f32 v41, v14, v15
	v_cvt_pk_bf16_f32 v42, v16, v17
	v_cvt_pk_bf16_f32 v43, v18, v19
	v_cvt_pk_bf16_f32 v44, v20, v21
	v_cvt_pk_bf16_f32 v45, v22, v23
	v_cvt_pk_bf16_f32 v46, v24, v25
	v_cvt_pk_bf16_f32 v47, v26, v27
	v_cvt_pk_bf16_f32 v48, v28, v29
	v_cvt_pk_bf16_f32 v49, v30, v31
	v_cvt_pk_bf16_f32 v50, v32, v33
	v_cvt_pk_bf16_f32 v51, v34, v35
	s_waitcnt lgkmcnt(7)
	v_pk_mul_f32 v[4:5], v[4:5], v[128:129]
	v_pk_mul_f32 v[6:7], v[6:7], v[130:131]
	v_pk_mul_f32 v[8:9], v[8:9], v[132:133]
	v_pk_mul_f32 v[10:11], v[10:11], v[134:135]
	v_pk_mul_f32 v[12:13], v[12:13], v[136:137]
	v_pk_mul_f32 v[14:15], v[14:15], v[138:139]
	v_pk_mul_f32 v[16:17], v[16:17], v[140:141]
	v_pk_mul_f32 v[18:19], v[18:19], v[142:143]
	v_pk_mul_f32 v[20:21], v[20:21], v[144:145]
	v_pk_mul_f32 v[22:23], v[22:23], v[146:147]
	v_pk_mul_f32 v[24:25], v[24:25], v[148:149]
	v_pk_mul_f32 v[26:27], v[26:27], v[150:151]
	v_pk_mul_f32 v[28:29], v[28:29], v[152:153]
	v_pk_mul_f32 v[30:31], v[30:31], v[154:155]
	v_pk_mul_f32 v[32:33], v[32:33], v[156:157]
	v_pk_mul_f32 v[34:35], v[34:35], v[158:159]
	ds_read_b128 v[72:75], v1 offset:2048
	ds_read_b128 v[88:91], v1 offset:6144
	ds_read_b128 v[76:79], v1 offset:3072
	ds_read_b128 v[92:95], v1 offset:7168
	ds_read_b128 v[96:99], v1 offset:8192
	ds_read_b128 v[100:103], v1 offset:9216
	ds_read_b128 v[104:107], v1 offset:10240
	ds_read_b128 v[108:111], v1 offset:11264
	ds_read_b128 v[112:115], v1 offset:12288
	ds_read_b128 v[116:119], v1 offset:13312
	ds_read_b128 v[120:123], v1 offset:14336
	ds_read_b128 v[124:127], v1 offset:15360
	s_waitcnt lgkmcnt(15)
	v_mfma_f32_16x16x32_bf16 v[164:167], v[56:59], v[52:55], 0
	v_mfma_f32_16x16x32_bf16 v[168:171], v[60:63], v[52:55], 0
	v_mfma_f32_16x16x32_bf16 v[164:167], v[64:67], v[36:39], v[164:167]
	s_waitcnt lgkmcnt(14)
	v_mfma_f32_16x16x32_bf16 v[168:171], v[80:83], v[36:39], v[168:171]
	s_waitcnt lgkmcnt(13)
	v_mfma_f32_16x16x32_bf16 v[164:167], v[68:71], v[40:43], v[164:167]
	s_waitcnt lgkmcnt(12)
	v_mfma_f32_16x16x32_bf16 v[168:171], v[84:87], v[40:43], v[168:171]
	s_waitcnt lgkmcnt(11)
	v_mfma_f32_16x16x32_bf16 v[164:167], v[72:75], v[44:47], v[164:167]
	s_waitcnt lgkmcnt(10)
	v_mfma_f32_16x16x32_bf16 v[168:171], v[88:91], v[44:47], v[168:171]
	s_waitcnt lgkmcnt(9)
	v_mfma_f32_16x16x32_bf16 v[164:167], v[76:79], v[48:51], v[164:167]
	s_waitcnt lgkmcnt(8)
	v_mfma_f32_16x16x32_bf16 v[168:171], v[92:95], v[48:51], v[168:171]
	s_waitcnt lgkmcnt(7)
	v_mfma_f32_16x16x32_bf16 v[4:7], v[96:99], v[52:55], v[4:7]
	s_waitcnt lgkmcnt(6)
	v_mfma_f32_16x16x32_bf16 v[8:11], v[100:103], v[52:55], v[8:11]
	s_waitcnt lgkmcnt(5)
	v_mfma_f32_16x16x32_bf16 v[12:15], v[104:107], v[52:55], v[12:15]
	s_waitcnt lgkmcnt(4)
	v_mfma_f32_16x16x32_bf16 v[16:19], v[108:111], v[52:55], v[16:19]
	s_waitcnt lgkmcnt(3)
	v_mfma_f32_16x16x32_bf16 v[20:23], v[112:115], v[52:55], v[20:23]
	s_waitcnt lgkmcnt(2)
	v_mfma_f32_16x16x32_bf16 v[24:27], v[116:119], v[52:55], v[24:27]
	s_waitcnt lgkmcnt(1)
	v_mfma_f32_16x16x32_bf16 v[28:31], v[120:123], v[52:55], v[28:31]
	s_waitcnt lgkmcnt(0)
	v_mfma_f32_16x16x32_bf16 v[32:35], v[124:127], v[52:55], v[32:35]
	global_store_dword v172, v164, s[36:37]
	global_store_dword v172, v165, s[36:37] offset:2048
	global_store_dword v173, v166, s[36:37]
	global_store_dword v173, v167, s[36:37] offset:2048
	global_store_dword v174, v168, s[36:37]
	global_store_dword v174, v169, s[36:37] offset:2048
	global_store_dword v175, v170, s[36:37]
	global_store_dword v175, v171, s[36:37] offset:2048
	s_add_u32 s36, s36, 0x10000
	s_addc_u32 s37, s37, 0
	s_add_i32 s60, s60, 21504
	s_cmp_lt_u32 s60, 129024
	s_cselect_b32 s60, s60, 0
	s_add_i32 s62, s62, 1
	s_waitcnt lgkmcnt(0)
	s_barrier
	s_cmp_lt_u32 s62, 64
	s_cbranch_scc1 .Lscan_act_loop
	s_nop 7
	s_and_b32 s3, s2, 7
	s_lshl_b32 s3, s3, 2
	s_lshr_b32 s6, s2, 5
	s_add_i32 s3, s3, s6
	s_lshl_b32 s3, s3, 16
	s_add_u32 s6, s20, 0x4400000
	s_addc_u32 s7, s21, 0
	s_add_u32 s6, s6, s3
	s_addc_u32 s7, s7, 0
	global_store_dword v176, v4, s[6:7]
	global_store_dword v176, v5, s[6:7] offset:512
	global_store_dword v176, v6, s[6:7] offset:1024
	global_store_dword v176, v7, s[6:7] offset:1536
	v_add_u32_e32 v176, 0x2000, v176
	global_store_dword v176, v8, s[6:7]
	global_store_dword v176, v9, s[6:7] offset:512
	global_store_dword v176, v10, s[6:7] offset:1024
	global_store_dword v176, v11, s[6:7] offset:1536
	v_add_u32_e32 v176, 0x2000, v176
	global_store_dword v176, v12, s[6:7]
	global_store_dword v176, v13, s[6:7] offset:512
	global_store_dword v176, v14, s[6:7] offset:1024
	global_store_dword v176, v15, s[6:7] offset:1536
	v_add_u32_e32 v176, 0x2000, v176
	global_store_dword v176, v16, s[6:7]
	global_store_dword v176, v17, s[6:7] offset:512
	global_store_dword v176, v18, s[6:7] offset:1024
	global_store_dword v176, v19, s[6:7] offset:1536
	v_add_u32_e32 v176, 0x2000, v176
	global_store_dword v176, v20, s[6:7]
	global_store_dword v176, v21, s[6:7] offset:512
	global_store_dword v176, v22, s[6:7] offset:1024
	global_store_dword v176, v23, s[6:7] offset:1536
	v_add_u32_e32 v176, 0x2000, v176
	global_store_dword v176, v24, s[6:7]
	global_store_dword v176, v25, s[6:7] offset:512
	global_store_dword v176, v26, s[6:7] offset:1024
	global_store_dword v176, v27, s[6:7] offset:1536
	v_add_u32_e32 v176, 0x2000, v176
	global_store_dword v176, v28, s[6:7]
	global_store_dword v176, v29, s[6:7] offset:512
	global_store_dword v176, v30, s[6:7] offset:1024
	global_store_dword v176, v31, s[6:7] offset:1536
	v_add_u32_e32 v176, 0x2000, v176
	global_store_dword v176, v32, s[6:7]
	global_store_dword v176, v33, s[6:7] offset:512
	global_store_dword v176, v34, s[6:7] offset:1024
	global_store_dword v176, v35, s[6:7] offset:1536
	s_branch .Lscan_join
